# P2 fused chunk epilogue: 16 unneeded s_nop in the DPP first-row fix-up removed
# baseline (speedup 1.0000x reference)
.LBB0_728:
	s_or_b64 exec, exec, s[12:13]
	v_readfirstlane_b32 s14, v0
	s_cmp_ge_i32 s14, s22
	s_mov_b64 s[12:13], -1
	s_cbranch_scc1 .LBB0_723
	s_cmp_ge_i32 s14, s21
	v_lshlrev_b32_e32 v92, 1, v138
	v_mbcnt_hi_u32_b32 v102, -1, v220
	s_cbranch_scc0 .LBB0_731
	s_sub_i32 s12, s14, s21
	s_and_b32 s15, s12, 3
	s_lshl_b32 s13, s15, 5
	v_or_b32_e32 v0, s13, v154
	s_lshr_b32 s12, s12, 2
	v_ashrrev_i32_e32 v1, 31, v0
	v_readlane_b32 s24, v254, 54
	v_lshlrev_b64 v[84:85], 12, v[0:1]
	v_readlane_b32 s25, v254, 55
	s_add_i32 s12, s12, s23
	v_mov_b32_e32 v93, v131
	v_lshl_add_u64 v[0:1], s[24:25], 0, v[84:85]
	s_lshl_b32 s24, s12, 7
	s_mov_b32 s25, s92
	v_lshl_add_u64 v[0:1], v[0:1], 0, s[24:25]
	v_lshl_add_u64 v[90:91], v[0:1], 0, v[92:93]
	global_load_dwordx4 v[68:71], v[90:91], off
	global_load_dwordx4 v[64:67], v[90:91], off offset:32
	s_add_i32 s93, s15, 1
	v_lshl_or_b32 v4, s93, 5, v136
	v_mad_u32_u24 v94, v4, s16, v129
	ds_read_b128 v[16:19], v94
	ds_read_b128 v[76:79], v94 offset:32
	s_add_i32 s94, s15, 2
	v_lshl_or_b32 v20, s94, 5, v136
	v_mad_u32_u24 v95, v20, s16, v129
	v_or_b32_e32 v2, s13, v136
	s_add_i32 s95, s15, 3
	v_mad_u32_u24 v93, v2, s16, v129
	v_lshl_or_b32 v20, s95, 5, v136
	ds_read_b128 v[0:3], v93
	ds_read_b128 v[72:75], v93 offset:32
	v_mad_u32_u24 v96, v20, s16, v129
	s_mov_b32 s13, s92
	v_readlane_b32 s56, v254, 22
	s_or_b32 s24, s15, 4
	s_lshl_b64 vcc, s[12:13], 2
	v_readlane_b32 s58, v254, 24
	v_readlane_b32 s59, v254, 25
	s_add_u32 vcc_lo, s58, vcc_lo
	s_addc_u32 vcc_hi, s59, vcc_hi
	s_cmp_eq_u32 s15, 3
	v_readlane_b32 s57, v254, 23
	v_readlane_b32 s56, v255, 4
	v_readlane_b32 s57, v255, 5
	v_readlane_b32 s60, v254, 26
	v_readlane_b32 s61, v254, 27
	v_readlane_b32 s62, v254, 28
	v_readlane_b32 s63, v254, 29
	v_readlane_b32 s64, v254, 30
	v_readlane_b32 s65, v254, 31
	v_readlane_b32 s66, v254, 32
	v_readlane_b32 s67, v254, 33
	v_readlane_b32 s68, v254, 34
	v_readlane_b32 s69, v254, 35
	v_readlane_b32 s70, v254, 36
	v_readlane_b32 s71, v254, 37
	s_waitcnt vmcnt(1) lgkmcnt(3)
	v_mfma_f32_32x32x16_bf16 v[48:63], v[16:19], v[68:71], 0
	ds_read_b128 v[16:19], v95
	ds_read_b128 v[80:83], v95 offset:32
	s_waitcnt lgkmcnt(1)
	v_mfma_f32_32x32x16_bf16 v[32:47], v[16:19], v[68:71], 0
	ds_read_b128 v[16:19], v96
	ds_read_b128 v[86:89], v96 offset:32
	s_waitcnt vmcnt(0)
	v_mfma_f32_32x32x16_bf16 v[48:63], v[76:79], v[64:67], v[48:63]
	global_load_dwordx4 v[76:79], v[90:91], off offset:64
	v_mfma_f32_32x32x16_bf16 v[0:15], v[0:3], v[68:71], 0
	v_mfma_f32_32x32x16_bf16 v[0:15], v[72:75], v[64:67], v[0:15]
	global_load_dwordx4 v[72:75], v[90:91], off offset:96
	s_waitcnt lgkmcnt(1)
	v_mfma_f32_32x32x16_bf16 v[16:31], v[16:19], v[68:71], 0
	v_mfma_f32_32x32x16_bf16 v[32:47], v[80:83], v[64:67], v[32:47]
	s_waitcnt lgkmcnt(0)
	v_mfma_f32_32x32x16_bf16 v[16:31], v[86:89], v[64:67], v[16:31]
	ds_read_b128 v[86:89], v93 offset:64
	ds_read_b128 v[80:83], v93 offset:96
	s_waitcnt vmcnt(1) lgkmcnt(1)
	v_mfma_f32_32x32x16_bf16 v[0:15], v[86:89], v[76:79], v[0:15]
	ds_read_b128 v[86:89], v94 offset:64
	ds_read_b128 v[98:101], v94 offset:96
	s_waitcnt lgkmcnt(1)
	v_mfma_f32_32x32x16_bf16 v[48:63], v[86:89], v[76:79], v[48:63]
	ds_read_b128 v[86:89], v95 offset:64
	ds_read_b128 v[104:107], v95 offset:96
	s_waitcnt lgkmcnt(1)
	v_mfma_f32_32x32x16_bf16 v[32:47], v[86:89], v[76:79], v[32:47]
	ds_read_b128 v[86:89], v96 offset:64
	ds_read_b128 v[112:115], v96 offset:96
	global_load_dword v96, v131, vcc
	s_mov_b32 s62, 0x6e80000
	s_mov_b32 s63, 0
	s_mov_b32 s64, 0x4c80000
	s_mov_b32 s65, 0
	s_mov_b32 s66, 0x2a80000
	s_mov_b32 s67, 0
	v_lshl_add_u64 v[190:191], v[90:91], 0, s[62:63]
	global_load_dwordx4 v[222:225], v[190:191], off
	global_load_dwordx4 v[226:229], v[190:191], off offset:32
	global_load_dwordx4 v[230:233], v[190:191], off offset:64
	global_load_dwordx4 v[234:237], v[190:191], off offset:96
	v_lshl_add_u64 v[190:191], v[90:91], 0, s[64:65]
	global_load_dwordx4 v[238:241], v[190:191], off
	global_load_dwordx4 v[242:245], v[190:191], off offset:32
	global_load_dwordx4 v[246:249], v[190:191], off offset:64
	global_load_dwordx4 v[250:253], v[190:191], off offset:96
	v_lshl_add_u64 v[190:191], v[90:91], 0, s[66:67]
	global_load_dwordx4 v[182:185], v[190:191], off
	global_load_dwordx4 v[186:189], v[190:191], off offset:32
	global_load_dwordx4 v[202:205], v[190:191], off offset:64
	global_load_dwordx4 v[206:209], v[190:191], off offset:96
	s_mov_b32 s66, 0x2a7e000
	s_mov_b32 s70, 3
	s_mov_b32 s71, 3
	s_mov_b64 s[68:69], exec
	v_lshl_add_u64 v[190:191], v[90:91], 0, s[66:67]
	s_mov_b64 exec, s[70:71]
	global_load_dwordx4 v[144:147], v[190:191], off
	global_load_dwordx4 v[148:151], v[190:191], off offset:32
	global_load_dwordx4 v[192:195], v[190:191], off offset:64
	global_load_dwordx4 v[196:199], v[190:191], off offset:96
	s_mov_b64 exec, s[68:69]
	s_cselect_b64 vcc, -1, 0
	s_or_b64 vcc, s[8:9], vcc
	s_xor_b32 s13, s15, 2
	s_cmp_lt_u32 s13, 2
	s_waitcnt lgkmcnt(1)
	v_mfma_f32_32x32x16_bf16 v[16:31], v[86:89], v[76:79], v[16:31]
	s_waitcnt vmcnt(17)
	v_mfma_f32_32x32x16_bf16 v[48:63], v[98:101], v[72:75], v[48:63]
	v_mfma_f32_32x32x16_bf16 v[32:47], v[104:107], v[72:75], v[32:47]
	s_nop 10
	v_cndmask_b32_e32 v48, v179, v48, vcc
	v_cndmask_b32_e32 v49, v179, v49, vcc
	v_cndmask_b32_e32 v50, v179, v50, vcc
	v_cndmask_b32_e32 v51, v179, v51, vcc
	v_cndmask_b32_e32 v52, v179, v52, vcc
	v_cndmask_b32_e32 v53, v179, v53, vcc
	v_cndmask_b32_e32 v54, v179, v54, vcc
	s_waitcnt lgkmcnt(0)
	v_mfma_f32_32x32x16_bf16 v[16:31], v[112:115], v[72:75], v[16:31]
	v_cndmask_b32_e32 v55, v179, v55, vcc
	v_cndmask_b32_e32 v56, v179, v56, vcc
	v_cndmask_b32_e32 v57, v179, v57, vcc
	v_cndmask_b32_e32 v58, v179, v58, vcc
	v_cndmask_b32_e32 v59, v179, v59, vcc
	v_cndmask_b32_e32 v60, v179, v60, vcc
	v_cndmask_b32_e32 v61, v179, v61, vcc
	v_cndmask_b32_e32 v62, v179, v62, vcc
	v_cndmask_b32_e32 v116, v179, v63, vcc
	s_cselect_b64 vcc, -1, 0
	s_or_b64 vcc, s[8:9], vcc
	s_or_b32 s13, s15, s20
	s_cmp_eq_u32 s13, 0
	v_cndmask_b32_e32 v117, v179, v32, vcc
	v_cndmask_b32_e32 v118, v179, v33, vcc
	v_cndmask_b32_e32 v119, v179, v34, vcc
	v_cndmask_b32_e32 v120, v179, v35, vcc
	v_cndmask_b32_e32 v121, v179, v36, vcc
	v_cndmask_b32_e32 v122, v179, v37, vcc
	v_cndmask_b32_e32 v123, v179, v38, vcc
	v_cndmask_b32_e32 v130, v179, v39, vcc
	v_cndmask_b32_e32 v63, v179, v40, vcc
	v_cndmask_b32_e32 v111, v179, v41, vcc
	v_cndmask_b32_e32 v110, v179, v42, vcc
	v_cndmask_b32_e32 v109, v179, v43, vcc
	v_cndmask_b32_e32 v108, v179, v44, vcc
	v_cndmask_b32_e32 v107, v179, v45, vcc
	v_cndmask_b32_e32 v106, v179, v46, vcc
	v_cndmask_b32_e32 v105, v179, v47, vcc
	s_cselect_b64 vcc, -1, 0
	v_cndmask_b32_e32 v103, v17, v179, vcc
	v_and_b32_e32 v17, 64, v102
	v_cndmask_b32_e32 v104, v16, v179, vcc
	v_xor_b32_e32 v16, 32, v102
	v_add_u32_e32 v17, 64, v17
	v_cndmask_b32_e32 v101, v18, v179, vcc
	v_cndmask_b32_e32 v100, v19, v179, vcc
	v_cndmask_b32_e32 v99, v20, v179, vcc
	v_cndmask_b32_e32 v98, v21, v179, vcc
	v_cndmask_b32_e32 v97, v22, v179, vcc
	v_cndmask_b32_e32 v95, v23, v179, vcc
	v_cndmask_b32_e32 v94, v24, v179, vcc
	v_cndmask_b32_e32 v93, v25, v179, vcc
	v_cndmask_b32_e32 v91, v26, v179, vcc
	v_cndmask_b32_e32 v90, v27, v179, vcc
	v_cndmask_b32_e32 v86, v28, v179, vcc
	v_cndmask_b32_e32 v87, v29, v179, vcc
	v_cndmask_b32_e32 v88, v30, v179, vcc
	v_cndmask_b32_e32 v89, v31, v179, vcc
	v_cmp_lt_i32_e32 vcc, v16, v17
	v_mfma_f32_32x32x16_bf16 v[0:15], v[80:83], v[72:75], v[0:15]
	s_mov_b32 s13, 0x3fb8aa3b
	v_cndmask_b32_e32 v44, v102, v16, vcc
	v_lshl_or_b32 v16, s24, 5, v136
	v_mad_u32_u24 v40, v16, s16, v129
	ds_read_b128 v[16:19], v40
	ds_read_b128 v[32:35], v40 offset:32
	ds_read_b128 v[36:39], v40 offset:64
	ds_read_b128 v[40:43], v40 offset:96
	v_lshlrev_b32_e32 v112, 2, v44
	s_waitcnt lgkmcnt(3)
	v_mfma_f32_32x32x16_bf16 v[16:31], v[16:19], v[68:71], 0
	s_nop 0
	v_cndmask_b32_e64 v0, v179, v0, s[26:27]
	v_cndmask_b32_e64 v1, v179, v1, s[28:29]
	v_max3_f32 v45, v0, s17, v1
	v_cndmask_b32_e64 v2, v179, v2, s[30:31]
	v_cndmask_b32_e64 v3, v179, v3, s[34:35]
	v_cndmask_b32_e64 v4, v179, v4, s[36:37]
	v_cndmask_b32_e64 v5, v179, v5, s[38:39]
	s_waitcnt lgkmcnt(2)
	v_mfma_f32_32x32x16_bf16 v[16:31], v[32:35], v[64:67], v[16:31]
	v_max3_f32 v32, v45, v2, v3
	v_max3_f32 v32, v32, v4, v5
	v_cndmask_b32_e64 v6, v179, v6, s[96:97]
	v_cndmask_b32_e64 v7, v179, v7, s[2:3]
	v_max3_f32 v32, v32, v6, v7
	v_cndmask_b32_e64 v8, v179, v8, s[72:73]
	v_cndmask_b32_e64 v9, v179, v9, s[74:75]
	s_waitcnt lgkmcnt(1)
	v_mfma_f32_32x32x16_bf16 v[16:31], v[36:39], v[76:79], v[16:31]
	v_max3_f32 v32, v32, v8, v9
	v_cndmask_b32_e64 v34, v179, v10, s[76:77]
	v_cndmask_b32_e64 v11, v179, v11, s[78:79]
	v_max3_f32 v10, v32, v34, v11
	v_cndmask_b32_e64 v12, v179, v12, s[80:81]
	v_cndmask_b32_e64 v13, v179, v13, s[82:83]
	v_max3_f32 v10, v10, v12, v13
	s_waitcnt lgkmcnt(0)
	v_mfma_f32_32x32x16_bf16 v[16:31], v[40:43], v[72:75], v[16:31]
	v_cndmask_b32_e64 v14, v179, v14, s[84:85]
	v_cndmask_b32_e64 v15, v179, v15, s[86:87]
	v_max3_f32 v10, v10, v14, v15
	v_max3_f32 v10, v10, v48, v49
	v_max3_f32 v10, v10, v50, v51
	v_max3_f32 v10, v10, v52, v53
	v_max3_f32 v10, v10, v54, v55
	s_nop 4
	v_cndmask_b32_e64 v16, v16, v179, s[56:57]
	v_readlane_b32 s56, v255, 34
	v_readlane_b32 s57, v255, 35
	v_max3_f32 v10, v10, v56, v57
	v_max3_f32 v10, v10, v58, v59
	v_cndmask_b32_e64 v17, v179, v17, s[56:57]
	v_readlane_b32 s56, v255, 8
	v_readlane_b32 s57, v255, 9
	v_max3_f32 v10, v10, v60, v61
	v_max3_f32 v10, v10, v62, v116
	v_cndmask_b32_e64 v18, v18, v179, s[56:57]
	v_readlane_b32 s56, v255, 10
	v_readlane_b32 s57, v255, 11
	v_max3_f32 v10, v10, v117, v118
	v_max3_f32 v10, v10, v119, v120
	v_cndmask_b32_e64 v19, v19, v179, s[56:57]
	v_readlane_b32 s56, v255, 12
	v_readlane_b32 s57, v255, 13
	v_max3_f32 v10, v10, v121, v122
	v_max3_f32 v10, v10, v123, v130
	v_cndmask_b32_e64 v20, v20, v179, s[56:57]
	v_readlane_b32 s56, v255, 14
	v_readlane_b32 s57, v255, 15
	v_max3_f32 v10, v10, v63, v111
	v_max3_f32 v10, v10, v110, v109
	v_cndmask_b32_e64 v21, v21, v179, s[56:57]
	v_readlane_b32 s56, v255, 16
	v_readlane_b32 s57, v255, 17
	v_max3_f32 v10, v10, v108, v107
	v_max3_f32 v10, v10, v106, v105
	v_cndmask_b32_e64 v22, v22, v179, s[56:57]
	v_readlane_b32 s56, v255, 18
	v_readlane_b32 s57, v255, 19
	v_max3_f32 v10, v10, v104, v103
	v_max3_f32 v10, v10, v101, v100
	v_cndmask_b32_e64 v23, v23, v179, s[56:57]
	v_readlane_b32 s56, v255, 20
	v_readlane_b32 s57, v255, 21
	v_max3_f32 v10, v10, v99, v98
	v_max3_f32 v10, v10, v97, v95
	v_cndmask_b32_e64 v24, v24, v179, s[56:57]
	v_readlane_b32 s56, v255, 22
	v_readlane_b32 s57, v255, 23
	v_max3_f32 v10, v10, v94, v93
	v_max3_f32 v10, v10, v91, v90
	v_cndmask_b32_e64 v25, v25, v179, s[56:57]
	v_readlane_b32 s56, v255, 24
	v_readlane_b32 s57, v255, 25
	v_max3_f32 v10, v10, v86, v87
	v_max3_f32 v10, v10, v88, v89
	v_cndmask_b32_e64 v26, v26, v179, s[56:57]
	v_readlane_b32 s56, v255, 26
	v_readlane_b32 s57, v255, 27
	v_max3_f32 v10, v10, v16, v17
	v_max3_f32 v10, v10, v18, v19
	v_cndmask_b32_e64 v27, v27, v179, s[56:57]
	v_readlane_b32 s56, v255, 28
	v_readlane_b32 s57, v255, 29
	v_max3_f32 v10, v10, v20, v21
	v_max3_f32 v10, v10, v22, v23
	v_cndmask_b32_e64 v28, v28, v179, s[56:57]
	v_readlane_b32 s56, v255, 30
	v_readlane_b32 s57, v255, 31
	v_max3_f32 v10, v10, v24, v25
	v_max3_f32 v10, v10, v26, v27
	v_cndmask_b32_e64 v29, v29, v179, s[56:57]
	v_readlane_b32 s56, v255, 32
	v_readlane_b32 s57, v255, 33
	v_max3_f32 v10, v10, v28, v29
	s_waitcnt vmcnt(16)
	v_mul_f32_e32 v33, 0x3fb8aa3b, v96
	v_cndmask_b32_e64 v30, v30, v179, s[56:57]
	v_readlane_b32 s56, v255, 2
	v_readlane_b32 s57, v255, 3
	v_lshl_add_u32 v115, s93, 6, v139
	v_lshl_or_b32 v114, s12, 6, v137
	v_cndmask_b32_e64 v31, v31, v179, s[56:57]
	v_max3_f32 v10, v10, v30, v31
	ds_bpermute_b32 v32, v112, v10
	s_waitcnt lgkmcnt(0)
	v_max_f32_e32 v32, v32, v32
	v_max_f32_e32 v10, v10, v32
	v_mul_f32_e32 v10, 0x3e38aa3b, v10
	v_max_f32_e32 v10, v10, v33
	v_fma_f32 v0, v0, s18, -v10
	v_exp_f32_e32 v0, v0
	v_fma_f32 v1, v1, s18, -v10
	v_exp_f32_e32 v1, v1
	v_fma_f32 v2, v2, s18, -v10
	v_exp_f32_e32 v2, v2
	v_fma_f32 v3, v3, s18, -v10
	v_exp_f32_e32 v3, v3
	v_fma_f32 v4, v4, s18, -v10
	v_add_f32_e32 v32, 0, v0
	v_exp_f32_e32 v4, v4
	v_fma_f32 v5, v5, s18, -v10
	v_add_f32_e32 v32, v1, v32
	v_exp_f32_e32 v5, v5
	v_fma_f32 v6, v6, s18, -v10
	v_add_f32_e32 v32, v2, v32
	v_exp_f32_e32 v6, v6
	v_fma_f32 v7, v7, s18, -v10
	v_add_f32_e32 v32, v3, v32
	v_exp_f32_e32 v7, v7
	v_add_f32_e32 v32, v4, v32
	v_add_f32_e32 v32, v5, v32
	v_add_f32_e32 v32, v6, v32
	v_fma_f32 v8, v8, s18, -v10
	v_add_f32_e32 v36, v7, v32
	v_exp_f32_e32 v32, v8
	v_fma_f32 v8, v9, s18, -v10
	v_exp_f32_e32 v33, v8
	v_fma_f32 v8, v34, s18, -v10
	v_exp_f32_e32 v34, v8
	v_fma_f32 v8, v11, s18, -v10
	v_exp_f32_e32 v35, v8
	v_fma_f32 v9, v12, s18, -v10
	v_add_f32_e32 v8, v32, v36
	v_exp_f32_e32 v36, v9
	v_fma_f32 v9, v13, s18, -v10
	v_add_f32_e32 v8, v33, v8
	v_exp_f32_e32 v37, v9
	v_fma_f32 v9, v14, s18, -v10
	v_add_f32_e32 v8, v34, v8
	v_exp_f32_e32 v38, v9
	v_fma_f32 v9, v15, s18, -v10
	v_add_f32_e32 v8, v35, v8
	v_exp_f32_e32 v40, v9
	v_fma_f32 v9, v48, s18, -v10
	v_add_f32_e32 v8, v36, v8
	v_exp_f32_e32 v39, v9
	v_fma_f32 v9, v49, s18, -v10
	v_add_f32_e32 v8, v37, v8
	v_exp_f32_e32 v41, v9
	v_fma_f32 v9, v50, s18, -v10
	v_add_f32_e32 v8, v38, v8
	v_exp_f32_e32 v42, v9
	v_fma_f32 v9, v51, s18, -v10
	v_add_f32_e32 v8, v40, v8
	v_exp_f32_e32 v43, v9
	v_fma_f32 v9, v52, s18, -v10
	v_add_f32_e32 v8, v39, v8
	v_exp_f32_e32 v44, v9
	v_fma_f32 v9, v53, s18, -v10
	v_add_f32_e32 v8, v41, v8
	v_exp_f32_e32 v45, v9
	v_fma_f32 v9, v54, s18, -v10
	v_add_f32_e32 v8, v42, v8
	v_exp_f32_e32 v46, v9
	v_fma_f32 v9, v55, s18, -v10
	v_add_f32_e32 v8, v43, v8
	v_exp_f32_e32 v48, v9
	v_fma_f32 v9, v56, s18, -v10
	v_add_f32_e32 v8, v44, v8
	v_exp_f32_e32 v47, v9
	v_fma_f32 v9, v57, s18, -v10
	v_add_f32_e32 v8, v45, v8
	v_exp_f32_e32 v49, v9
	v_fma_f32 v9, v58, s18, -v10
	v_add_f32_e32 v8, v46, v8
	v_exp_f32_e32 v50, v9
	v_fma_f32 v9, v59, s18, -v10
	v_add_f32_e32 v8, v48, v8
	v_exp_f32_e32 v51, v9
	v_fma_f32 v9, v60, s18, -v10
	v_add_f32_e32 v8, v47, v8
	v_exp_f32_e32 v52, v9
	v_fma_f32 v9, v61, s18, -v10
	v_add_f32_e32 v8, v49, v8
	v_exp_f32_e32 v53, v9
	v_fma_f32 v9, v62, s18, -v10
	v_add_f32_e32 v8, v50, v8
	v_exp_f32_e32 v54, v9
	v_fma_f32 v9, v116, s18, -v10
	v_add_f32_e32 v8, v51, v8
	v_exp_f32_e32 v56, v9
	v_fma_f32 v9, v117, s18, -v10
	v_add_f32_e32 v8, v52, v8
	v_exp_f32_e32 v55, v9
	v_fma_f32 v9, v118, s18, -v10
	v_add_f32_e32 v8, v53, v8
	v_exp_f32_e32 v57, v9
	v_fma_f32 v9, v119, s18, -v10
	v_add_f32_e32 v8, v54, v8
	v_exp_f32_e32 v58, v9
	v_fma_f32 v9, v120, s18, -v10
	v_add_f32_e32 v8, v56, v8
	v_exp_f32_e32 v59, v9
	v_fma_f32 v9, v121, s18, -v10
	v_add_f32_e32 v8, v55, v8
	v_exp_f32_e32 v60, v9
	v_fma_f32 v9, v122, s18, -v10
	v_add_f32_e32 v8, v57, v8
	v_exp_f32_e32 v61, v9
	v_fma_f32 v9, v123, s18, -v10
	v_add_f32_e32 v8, v58, v8
	v_exp_f32_e32 v62, v9
	v_fma_f32 v9, v130, s18, -v10
	v_add_f32_e32 v8, v59, v8
	v_exp_f32_e32 v64, v9
	v_fma_f32 v9, v63, s18, -v10
	v_add_f32_e32 v8, v60, v8
	v_exp_f32_e32 v63, v9
	v_fma_f32 v9, v111, s18, -v10
	v_add_f32_e32 v8, v61, v8
	v_exp_f32_e32 v65, v9
	v_fma_f32 v9, v110, s18, -v10
	v_add_f32_e32 v8, v62, v8
	v_exp_f32_e32 v66, v9
	v_fma_f32 v9, v109, s18, -v10
	v_add_f32_e32 v8, v64, v8
	v_exp_f32_e32 v67, v9
	v_fma_f32 v9, v108, s18, -v10
	v_add_f32_e32 v8, v63, v8
	v_exp_f32_e32 v68, v9
	v_fma_f32 v9, v107, s18, -v10
	v_add_f32_e32 v8, v65, v8
	v_exp_f32_e32 v69, v9
	v_fma_f32 v9, v106, s18, -v10
	v_add_f32_e32 v8, v66, v8
	v_exp_f32_e32 v70, v9
	v_fma_f32 v9, v105, s18, -v10
	v_add_f32_e32 v8, v67, v8
	v_exp_f32_e32 v72, v9
	v_fma_f32 v9, v104, s18, -v10
	v_add_f32_e32 v8, v68, v8
	v_exp_f32_e32 v71, v9
	v_fma_f32 v9, v103, s18, -v10
	v_add_f32_e32 v8, v69, v8
	v_exp_f32_e32 v73, v9
	v_fma_f32 v9, v101, s18, -v10
	v_add_f32_e32 v8, v70, v8
	v_exp_f32_e32 v74, v9
	v_fma_f32 v9, v100, s18, -v10
	v_add_f32_e32 v8, v72, v8
	v_exp_f32_e32 v75, v9
	v_fma_f32 v9, v99, s18, -v10
	v_add_f32_e32 v8, v71, v8
	v_exp_f32_e32 v76, v9
	v_fma_f32 v9, v98, s18, -v10
	v_add_f32_e32 v8, v73, v8
	v_exp_f32_e32 v77, v9
	v_fma_f32 v9, v97, s18, -v10
	v_add_f32_e32 v8, v74, v8
	v_exp_f32_e32 v78, v9
	v_fma_f32 v9, v95, s18, -v10
	v_add_f32_e32 v8, v75, v8
	v_exp_f32_e32 v80, v9
	v_fma_f32 v9, v94, s18, -v10
	v_add_f32_e32 v8, v76, v8
	v_exp_f32_e32 v79, v9
	v_fma_f32 v9, v93, s18, -v10
	v_add_f32_e32 v8, v77, v8
	v_exp_f32_e32 v81, v9
	v_fma_f32 v9, v91, s18, -v10
	v_add_f32_e32 v8, v78, v8
	v_exp_f32_e32 v82, v9
	v_fma_f32 v9, v90, s18, -v10
	v_add_f32_e32 v8, v80, v8
	v_exp_f32_e32 v83, v9
	v_fma_f32 v9, v86, s18, -v10
	v_add_f32_e32 v8, v79, v8
	v_exp_f32_e32 v86, v9
	v_fma_f32 v9, v87, s18, -v10
	v_add_f32_e32 v8, v81, v8
	v_exp_f32_e32 v87, v9
	v_fma_f32 v9, v88, s18, -v10
	v_add_f32_e32 v8, v82, v8
	v_exp_f32_e32 v88, v9
	v_fma_f32 v9, v89, s18, -v10
	v_add_f32_e32 v8, v83, v8
	v_exp_f32_e32 v90, v9
	v_fma_f32 v9, v16, s18, -v10
	v_add_f32_e32 v8, v86, v8
	v_exp_f32_e32 v89, v9
	v_fma_f32 v9, v17, s18, -v10
	v_add_f32_e32 v8, v87, v8
	v_exp_f32_e32 v91, v9
	v_fma_f32 v9, v18, s18, -v10
	v_add_f32_e32 v8, v88, v8
	v_exp_f32_e32 v93, v9
	v_fma_f32 v9, v19, s18, -v10
	v_add_f32_e32 v8, v90, v8
	v_exp_f32_e32 v94, v9
	v_fma_f32 v9, v20, s18, -v10
	v_add_f32_e32 v8, v89, v8
	v_exp_f32_e32 v95, v9
	v_fma_f32 v9, v21, s18, -v10
	v_add_f32_e32 v8, v91, v8
	v_exp_f32_e32 v97, v9
	v_fma_f32 v9, v22, s18, -v10
	v_add_f32_e32 v8, v93, v8
	v_exp_f32_e32 v98, v9
	v_fma_f32 v9, v23, s18, -v10
	v_add_f32_e32 v8, v94, v8
	v_exp_f32_e32 v100, v9
	v_fma_f32 v9, v24, s18, -v10
	v_add_f32_e32 v8, v95, v8
	v_exp_f32_e32 v99, v9
	v_fma_f32 v9, v25, s18, -v10
	v_add_f32_e32 v8, v97, v8
	v_exp_f32_e32 v101, v9
	v_fma_f32 v9, v26, s18, -v10
	v_add_f32_e32 v8, v98, v8
	v_exp_f32_e32 v103, v9
	v_fma_f32 v9, v27, s18, -v10
	v_add_f32_e32 v8, v100, v8
	v_exp_f32_e32 v104, v9
	v_fma_f32 v9, v28, s18, -v10
	v_add_f32_e32 v8, v99, v8
	v_exp_f32_e32 v105, v9
	v_fma_f32 v9, v29, s18, -v10
	v_add_f32_e32 v8, v101, v8
	v_exp_f32_e32 v106, v9
	v_fma_f32 v9, v30, s18, -v10
	v_add_f32_e32 v8, v103, v8
	v_exp_f32_e32 v107, v9
	v_fma_f32 v9, v31, s18, -v10
	v_add_f32_e32 v8, v104, v8
	v_exp_f32_e32 v108, v9
	v_add_f32_e32 v8, v105, v8
	v_add_f32_e32 v8, v106, v8
	v_add_f32_e32 v8, v107, v8
	v_add_f32_e32 v8, v108, v8
	ds_bpermute_b32 v9, v112, v8
	v_fma_f32 v10, v96, s13, -v10
	v_exp_f32_e32 v10, v10
	v_cvt_pk_bf16_f32 v0, v0, v1
	v_cvt_pk_bf16_f32 v1, v2, v3
	s_waitcnt lgkmcnt(0)
	v_add_f32_e32 v8, v8, v9
	v_add_f32_e32 v96, v10, v8
	v_div_scale_f32 v8, vcc, v96, v96, 1.0
	v_rcp_f32_e32 v9, v8
	v_cvt_pk_bf16_f32 v2, v4, v5
	v_cvt_pk_bf16_f32 v3, v6, v7
	v_cvt_pk_bf16_f32 v32, v32, v33
	v_fma_f32 v10, -v8, v9, 1.0
	v_fmac_f32_e32 v9, v10, v9
	v_div_scale_f32 v10, vcc, 1.0, v96, 1.0
	v_mul_f32_e32 v11, v10, v9
	v_fma_f32 v12, -v8, v11, v10
	v_fmac_f32_e32 v11, v12, v9
	v_fma_f32 v8, -v8, v11, v10
	v_lshl_add_u32 v12, s15, 6, v139
	v_div_fmas_f32 v109, v8, v9, v11
	v_add_u32_e32 v8, v12, v157
	v_add_u32_e32 v110, 0x9000, v8
	ds_read2_b64 v[8:11], v110 offset1:2
	v_add_u32_e32 v4, v12, v158
	v_add_u32_e32 v119, 0x9000, v4
	ds_read2_b64 v[110:113], v110 offset0:4 offset1:6
	s_waitcnt lgkmcnt(1)
	v_mfma_f32_32x32x16_bf16 v[16:31], v[8:11], v[0:3], 0
	ds_read2_b64 v[4:7], v119 offset1:2
	v_cvt_pk_bf16_f32 v33, v34, v35
	v_cvt_pk_bf16_f32 v34, v36, v37
	v_cvt_pk_bf16_f32 v35, v38, v40
	v_cvt_pk_bf16_f32 v36, v39, v41
	v_cvt_pk_bf16_f32 v37, v42, v43
	v_cvt_pk_bf16_f32 v38, v44, v45
	s_waitcnt lgkmcnt(1)
	v_mfma_f32_32x32x16_bf16 v[16:31], v[110:113], v[32:35], v[16:31]
	ds_read2_b64 v[110:113], v119 offset0:4 offset1:6
	v_cvt_pk_bf16_f32 v39, v46, v48
	v_lshl_add_u32 v116, s94, 6, v139
	v_lshl_add_u32 v117, s95, 6, v139
	v_lshl_add_u32 v118, s24, 6, v139
	v_readlane_b32 s12, v254, 52
	v_readlane_b32 s13, v254, 53
	s_waitcnt lgkmcnt(1)
	v_mfma_f32_32x32x16_bf16 v[0:15], v[4:7], v[0:3], 0
	v_lshlrev_b32_e32 v130, 1, v114
	s_waitcnt lgkmcnt(0)
	v_mfma_f32_32x32x16_bf16 v[0:15], v[110:113], v[32:35], v[0:15]
	v_add_u32_e32 v32, v115, v157
	v_add_u32_e32 v40, 0x9000, v32
	ds_read2_b64 v[32:35], v40 offset1:2
	s_waitcnt lgkmcnt(0)
	v_mfma_f32_32x32x16_bf16 v[16:31], v[32:35], v[36:39], v[16:31]
	v_add_u32_e32 v32, v115, v158
	v_add_u32_e32 v41, 0x9000, v32
	ds_read2_b64 v[32:35], v41 offset1:2
	s_waitcnt lgkmcnt(0)
	v_mfma_f32_32x32x16_bf16 v[0:15], v[32:35], v[36:39], v[0:15]
	ds_read2_b64 v[32:35], v40 offset0:4 offset1:6
	v_cvt_pk_bf16_f32 v36, v47, v49
	v_cvt_pk_bf16_f32 v37, v50, v51
	v_cvt_pk_bf16_f32 v38, v52, v53
	v_cvt_pk_bf16_f32 v39, v54, v56
	s_waitcnt lgkmcnt(0)
	s_nop 0
	v_mfma_f32_32x32x16_bf16 v[16:31], v[32:35], v[36:39], v[16:31]
	ds_read2_b64 v[32:35], v41 offset0:4 offset1:6
	s_waitcnt lgkmcnt(0)
	v_mfma_f32_32x32x16_bf16 v[0:15], v[32:35], v[36:39], v[0:15]
	v_add_u32_e32 v32, v116, v157
	v_add_u32_e32 v40, 0x9000, v32
	ds_read2_b64 v[32:35], v40 offset1:2
	v_cvt_pk_bf16_f32 v36, v55, v57
	v_cvt_pk_bf16_f32 v37, v58, v59
	v_cvt_pk_bf16_f32 v38, v60, v61
	v_cvt_pk_bf16_f32 v39, v62, v64
	s_waitcnt lgkmcnt(0)
	s_nop 0
	v_mfma_f32_32x32x16_bf16 v[16:31], v[32:35], v[36:39], v[16:31]
	v_add_u32_e32 v32, v116, v158
	v_add_u32_e32 v41, 0x9000, v32
	ds_read2_b64 v[32:35], v41 offset1:2
	s_waitcnt lgkmcnt(0)
	v_mfma_f32_32x32x16_bf16 v[0:15], v[32:35], v[36:39], v[0:15]
	ds_read2_b64 v[32:35], v40 offset0:4 offset1:6
	v_cvt_pk_bf16_f32 v36, v63, v65
	v_cvt_pk_bf16_f32 v37, v66, v67
	v_cvt_pk_bf16_f32 v38, v68, v69
	v_cvt_pk_bf16_f32 v39, v70, v72
	s_waitcnt lgkmcnt(0)
	s_nop 0
	v_mfma_f32_32x32x16_bf16 v[16:31], v[32:35], v[36:39], v[16:31]
	ds_read2_b64 v[32:35], v41 offset0:4 offset1:6
	s_waitcnt lgkmcnt(0)
	v_mfma_f32_32x32x16_bf16 v[0:15], v[32:35], v[36:39], v[0:15]
	v_add_u32_e32 v32, v117, v157
	v_add_u32_e32 v40, 0x9000, v32
	ds_read2_b64 v[32:35], v40 offset1:2
	v_cvt_pk_bf16_f32 v36, v71, v73
	v_cvt_pk_bf16_f32 v37, v74, v75
	v_cvt_pk_bf16_f32 v38, v76, v77
	v_cvt_pk_bf16_f32 v39, v78, v80
	s_waitcnt lgkmcnt(0)
	s_nop 0
	v_mfma_f32_32x32x16_bf16 v[16:31], v[32:35], v[36:39], v[16:31]
	v_add_u32_e32 v32, v117, v158
	v_add_u32_e32 v41, 0x9000, v32
	ds_read2_b64 v[32:35], v41 offset1:2
	s_waitcnt lgkmcnt(0)
	v_mfma_f32_32x32x16_bf16 v[0:15], v[32:35], v[36:39], v[0:15]
	ds_read2_b64 v[32:35], v40 offset0:4 offset1:6
	v_cvt_pk_bf16_f32 v36, v79, v81
	v_cvt_pk_bf16_f32 v37, v82, v83
	v_cvt_pk_bf16_f32 v38, v86, v87
	v_cvt_pk_bf16_f32 v39, v88, v90
	s_waitcnt lgkmcnt(0)
	s_nop 0
	v_mfma_f32_32x32x16_bf16 v[16:31], v[32:35], v[36:39], v[16:31]
	ds_read2_b64 v[32:35], v41 offset0:4 offset1:6
	s_waitcnt lgkmcnt(0)
	v_mfma_f32_32x32x16_bf16 v[0:15], v[32:35], v[36:39], v[0:15]
	v_add_u32_e32 v32, v118, v157
	v_add_u32_e32 v40, 0x9000, v32
	ds_read2_b64 v[32:35], v40 offset1:2
	v_cvt_pk_bf16_f32 v36, v89, v91
	v_cvt_pk_bf16_f32 v37, v93, v94
	v_cvt_pk_bf16_f32 v38, v95, v97
	v_cvt_pk_bf16_f32 v39, v98, v100
	s_waitcnt lgkmcnt(0)
	s_nop 0
	v_mfma_f32_32x32x16_bf16 v[16:31], v[32:35], v[36:39], v[16:31]
	v_add_u32_e32 v32, v118, v158
	v_add_u32_e32 v41, 0x9000, v32
	ds_read2_b64 v[32:35], v41 offset1:2
	s_waitcnt lgkmcnt(0)
	v_mfma_f32_32x32x16_bf16 v[0:15], v[32:35], v[36:39], v[0:15]
	ds_read2_b64 v[32:35], v40 offset0:4 offset1:6
	v_cvt_pk_bf16_f32 v36, v99, v101
	v_cvt_pk_bf16_f32 v37, v103, v104
	v_cvt_pk_bf16_f32 v38, v105, v106
	v_cvt_pk_bf16_f32 v39, v107, v108
	s_waitcnt lgkmcnt(0)
	s_nop 0
	v_mfma_f32_32x32x16_bf16 v[16:31], v[32:35], v[36:39], v[16:31]
	ds_read2_b64 v[32:35], v41 offset0:4 offset1:6
	s_waitcnt lgkmcnt(0)
	v_mfma_f32_32x32x16_bf16 v[0:15], v[32:35], v[36:39], v[0:15]
	v_div_fixup_f32 v32, v109, v96, 1.0
	v_lshl_add_u64 v[34:35], s[12:13], 0, v[84:85]
	s_nop 6
	v_pk_mul_f32 v[16:17], v[16:17], v[32:33] op_sel_hi:[1,0]
	v_pk_mul_f32 v[18:19], v[18:19], v[32:33] op_sel_hi:[1,0]
	v_pk_mul_f32 v[20:21], v[20:21], v[32:33] op_sel_hi:[1,0]
	v_pk_mul_f32 v[22:23], v[22:23], v[32:33] op_sel_hi:[1,0]
	v_pk_mul_f32 v[24:25], v[24:25], v[32:33] op_sel_hi:[1,0]
	v_pk_mul_f32 v[26:27], v[26:27], v[32:33] op_sel_hi:[1,0]
	v_pk_mul_f32 v[28:29], v[28:29], v[32:33] op_sel_hi:[1,0]
	v_pk_mul_f32 v[30:31], v[30:31], v[32:33] op_sel_hi:[1,0]
	v_and_b32_e32 v152, 32, v102
	v_lshrrev_b32_e32 v152, 2, v152
	v_mov_b32_e32 v153, 0
	v_lshl_add_u64 v[200:201], v[34:35], 0, v[130:131]
	v_pk_mul_f32 v[0:1], v[0:1], v[32:33] op_sel_hi:[1,0]
	v_pk_mul_f32 v[2:3], v[2:3], v[32:33] op_sel_hi:[1,0]
	v_pk_mul_f32 v[4:5], v[4:5], v[32:33] op_sel_hi:[1,0]
	v_pk_mul_f32 v[6:7], v[6:7], v[32:33] op_sel_hi:[1,0]
	v_pk_mul_f32 v[8:9], v[8:9], v[32:33] op_sel_hi:[1,0]
	v_pk_mul_f32 v[10:11], v[10:11], v[32:33] op_sel_hi:[1,0]
	v_pk_mul_f32 v[12:13], v[12:13], v[32:33] op_sel_hi:[1,0]
	v_pk_mul_f32 v[14:15], v[14:15], v[32:33] op_sel_hi:[1,0]
	v_cvt_pk_bf16_f32 v104, v16, v17
	v_cvt_pk_bf16_f32 v105, v18, v19
	v_cvt_pk_bf16_f32 v106, v20, v21
	v_cvt_pk_bf16_f32 v107, v22, v23
	v_cvt_pk_bf16_f32 v108, v24, v25
	v_cvt_pk_bf16_f32 v109, v26, v27
	v_cvt_pk_bf16_f32 v110, v28, v29
	v_cvt_pk_bf16_f32 v111, v30, v31
	v_cvt_pk_bf16_f32 v112, v0, v1
	v_cvt_pk_bf16_f32 v113, v2, v3
	v_cvt_pk_bf16_f32 v114, v4, v5
	v_cvt_pk_bf16_f32 v115, v6, v7
	v_cvt_pk_bf16_f32 v116, v8, v9
	v_cvt_pk_bf16_f32 v117, v10, v11
	v_cvt_pk_bf16_f32 v118, v12, v13
	v_cvt_pk_bf16_f32 v119, v14, v15
	v_lshl_add_u64 v[200:201], v[200:201], 0, v[152:153]
	s_lshl_b32 s66, s23, 8
	s_sub_i32 s66, 0x12000, s66
	s_mov_b32 s56, 1
	s_mov_b32 s57, 1
	s_mov_b32 s58, 3
	s_mov_b32 s59, 3
	v_add_u32_e32 v100, v130, v152
	v_lshlrev_b32_e32 v100, 1, v100
	v_add_u32_e32 v100, s66, v100
	v_lshrrev_b32_e32 v32, 12, v84
	v_cmp_gt_u32_e64 s[70:71], 1, v32
	v_cmp_gt_u32_e64 s[94:95], 2, v32
	s_cmp_eq_u64 s[94:95], 0
	v_permlane32_swap_b32_e32 v104, v106
	v_permlane32_swap_b32_e32 v105, v107
	v_permlane32_swap_b32_e32 v108, v110
	v_permlane32_swap_b32_e32 v109, v111
	v_permlane32_swap_b32_e32 v112, v114
	v_permlane32_swap_b32_e32 v113, v115
	v_permlane32_swap_b32_e32 v116, v118
	v_permlane32_swap_b32_e32 v117, v119
	ds_read_b128 v[36:39], v100
	ds_read_b128 v[40:43], v100 offset:16
	ds_read_b128 v[44:47], v100 offset:2048
	ds_read_b128 v[48:51], v100 offset:2064
	ds_read_b128 v[52:55], v100 offset:4096
	ds_read_b128 v[56:59], v100 offset:4112
	ds_read_b128 v[60:63], v100 offset:64
	ds_read_b128 v[64:67], v100 offset:80
	ds_read_b128 v[68:71], v100 offset:2112
	ds_read_b128 v[72:75], v100 offset:2128
	ds_read_b128 v[76:79], v100 offset:4160
	ds_read_b128 v[80:83], v100 offset:4176
	s_waitcnt vmcnt(0)
	v_mov_b32_dpp v0, v182 wave_shr:1 row_mask:0xf bank_mask:0xf
	v_mov_b32_dpp v1, v183 wave_shr:1 row_mask:0xf bank_mask:0xf
	v_mov_b32_dpp v2, v184 wave_shr:1 row_mask:0xf bank_mask:0xf
	v_mov_b32_dpp v3, v185 wave_shr:1 row_mask:0xf bank_mask:0xf
	v_mov_b32_dpp v4, v186 wave_shr:1 row_mask:0xf bank_mask:0xf
	v_mov_b32_dpp v5, v187 wave_shr:1 row_mask:0xf bank_mask:0xf
	v_mov_b32_dpp v6, v188 wave_shr:1 row_mask:0xf bank_mask:0xf
	v_mov_b32_dpp v7, v189 wave_shr:1 row_mask:0xf bank_mask:0xf
	v_mov_b32_dpp v8, v202 wave_shr:1 row_mask:0xf bank_mask:0xf
	v_mov_b32_dpp v9, v203 wave_shr:1 row_mask:0xf bank_mask:0xf
	v_mov_b32_dpp v10, v204 wave_shr:1 row_mask:0xf bank_mask:0xf
	v_mov_b32_dpp v11, v205 wave_shr:1 row_mask:0xf bank_mask:0xf
	v_mov_b32_dpp v12, v206 wave_shr:1 row_mask:0xf bank_mask:0xf
	v_mov_b32_dpp v13, v207 wave_shr:1 row_mask:0xf bank_mask:0xf
	v_mov_b32_dpp v14, v208 wave_shr:1 row_mask:0xf bank_mask:0xf
	v_mov_b32_dpp v15, v209 wave_shr:1 row_mask:0xf bank_mask:0xf
	v_mov_b32_dpp v16, v0 wave_shr:1 row_mask:0xf bank_mask:0xf
	v_mov_b32_dpp v17, v1 wave_shr:1 row_mask:0xf bank_mask:0xf
	v_mov_b32_dpp v18, v2 wave_shr:1 row_mask:0xf bank_mask:0xf
	v_mov_b32_dpp v19, v3 wave_shr:1 row_mask:0xf bank_mask:0xf
	v_mov_b32_dpp v20, v4 wave_shr:1 row_mask:0xf bank_mask:0xf
	v_mov_b32_dpp v21, v5 wave_shr:1 row_mask:0xf bank_mask:0xf
	v_mov_b32_dpp v22, v6 wave_shr:1 row_mask:0xf bank_mask:0xf
	v_mov_b32_dpp v23, v7 wave_shr:1 row_mask:0xf bank_mask:0xf
	v_mov_b32_dpp v24, v8 wave_shr:1 row_mask:0xf bank_mask:0xf
	v_mov_b32_dpp v25, v9 wave_shr:1 row_mask:0xf bank_mask:0xf
	v_mov_b32_dpp v26, v10 wave_shr:1 row_mask:0xf bank_mask:0xf
	v_mov_b32_dpp v27, v11 wave_shr:1 row_mask:0xf bank_mask:0xf
	v_mov_b32_dpp v28, v12 wave_shr:1 row_mask:0xf bank_mask:0xf
	v_mov_b32_dpp v29, v13 wave_shr:1 row_mask:0xf bank_mask:0xf
	v_mov_b32_dpp v30, v14 wave_shr:1 row_mask:0xf bank_mask:0xf
	v_mov_b32_dpp v31, v15 wave_shr:1 row_mask:0xf bank_mask:0xf
	v_mov_b32_dpp v96, v144 wave_shl:1 row_mask:0xf bank_mask:0xf
	v_cndmask_b32_e64 v16, v16, v144, s[58:59]
	v_cndmask_b32_e64 v0, v0, v96, s[56:57]
	v_mov_b32_dpp v97, v145 wave_shl:1 row_mask:0xf bank_mask:0xf
	v_cndmask_b32_e64 v17, v17, v145, s[58:59]
	v_cndmask_b32_e64 v1, v1, v97, s[56:57]
	v_mov_b32_dpp v96, v146 wave_shl:1 row_mask:0xf bank_mask:0xf
	v_cndmask_b32_e64 v18, v18, v146, s[58:59]
	v_cndmask_b32_e64 v2, v2, v96, s[56:57]
	v_mov_b32_dpp v97, v147 wave_shl:1 row_mask:0xf bank_mask:0xf
	v_cndmask_b32_e64 v19, v19, v147, s[58:59]
	v_cndmask_b32_e64 v3, v3, v97, s[56:57]
	v_mov_b32_dpp v96, v148 wave_shl:1 row_mask:0xf bank_mask:0xf
	v_cndmask_b32_e64 v20, v20, v148, s[58:59]
	v_cndmask_b32_e64 v4, v4, v96, s[56:57]
	v_mov_b32_dpp v97, v149 wave_shl:1 row_mask:0xf bank_mask:0xf
	v_cndmask_b32_e64 v21, v21, v149, s[58:59]
	v_cndmask_b32_e64 v5, v5, v97, s[56:57]
	v_mov_b32_dpp v96, v150 wave_shl:1 row_mask:0xf bank_mask:0xf
	v_cndmask_b32_e64 v22, v22, v150, s[58:59]
	v_cndmask_b32_e64 v6, v6, v96, s[56:57]
	v_mov_b32_dpp v97, v151 wave_shl:1 row_mask:0xf bank_mask:0xf
	v_cndmask_b32_e64 v23, v23, v151, s[58:59]
	v_cndmask_b32_e64 v7, v7, v97, s[56:57]
	v_mov_b32_dpp v96, v192 wave_shl:1 row_mask:0xf bank_mask:0xf
	v_cndmask_b32_e64 v24, v24, v192, s[58:59]
	v_cndmask_b32_e64 v8, v8, v96, s[56:57]
	v_mov_b32_dpp v97, v193 wave_shl:1 row_mask:0xf bank_mask:0xf
	v_cndmask_b32_e64 v25, v25, v193, s[58:59]
	v_cndmask_b32_e64 v9, v9, v97, s[56:57]
	v_mov_b32_dpp v96, v194 wave_shl:1 row_mask:0xf bank_mask:0xf
	v_cndmask_b32_e64 v26, v26, v194, s[58:59]
	v_cndmask_b32_e64 v10, v10, v96, s[56:57]
	v_mov_b32_dpp v97, v195 wave_shl:1 row_mask:0xf bank_mask:0xf
	v_cndmask_b32_e64 v27, v27, v195, s[58:59]
	v_cndmask_b32_e64 v11, v11, v97, s[56:57]
	v_mov_b32_dpp v96, v196 wave_shl:1 row_mask:0xf bank_mask:0xf
	v_cndmask_b32_e64 v28, v28, v196, s[58:59]
	v_cndmask_b32_e64 v12, v12, v96, s[56:57]
	v_mov_b32_dpp v97, v197 wave_shl:1 row_mask:0xf bank_mask:0xf
	v_cndmask_b32_e64 v29, v29, v197, s[58:59]
	v_cndmask_b32_e64 v13, v13, v97, s[56:57]
	v_mov_b32_dpp v96, v198 wave_shl:1 row_mask:0xf bank_mask:0xf
	v_cndmask_b32_e64 v30, v30, v198, s[58:59]
	v_cndmask_b32_e64 v14, v14, v96, s[56:57]
	v_mov_b32_dpp v97, v199 wave_shl:1 row_mask:0xf bank_mask:0xf
	v_cndmask_b32_e64 v31, v31, v199, s[58:59]
	v_cndmask_b32_e64 v15, v15, v97, s[56:57]
	s_waitcnt lgkmcnt(6)
	s_cbranch_scc1 .Lcf_nomask0
	v_cndmask_b32_e64 v0, v0, 0, s[70:71]
	v_cndmask_b32_e64 v16, v16, 0, s[94:95]
	v_cndmask_b32_e64 v1, v1, 0, s[70:71]
	v_cndmask_b32_e64 v17, v17, 0, s[94:95]
	v_cndmask_b32_e64 v2, v2, 0, s[70:71]
	v_cndmask_b32_e64 v18, v18, 0, s[94:95]
	v_cndmask_b32_e64 v3, v3, 0, s[70:71]
	v_cndmask_b32_e64 v19, v19, 0, s[94:95]
